# GEMM K-loops: first K-iteration peeled, its first MFMA per accumulator takes SrcC = inline 0, so the 128 v_mov that zeroed the accumulators in every unit header are gone (17 units per workgroup)
# speedup vs baseline: 1.0073x; 1.0073x over previous
.LBB0_201:
	s_ashr_i32 s75, s74, 31
	s_lshl_b64 s[2:3], s[74:75], 19
	s_add_u32 s76, s60, s2
	s_addc_u32 s77, s61, s3
	s_and_b64 s[2:3], s[8:9], exec
	s_cselect_b32 s1, s77, s13
	s_cselect_b32 s2, s76, s12
	s_ashr_i32 s73, s72, 31
	s_lshl_b64 s[34:35], s[72:73], 19
	s_add_u32 s78, s36, s34
	s_addc_u32 s79, s37, s35
	s_and_b64 s[34:35], s[8:9], exec
	s_cselect_b32 s3, s79, s81
	s_cselect_b32 s34, s78, s80
	s_add_u32 s12, s12, 0x40080
	s_addc_u32 s13, s13, 0
	s_add_u32 s35, s80, 0x100
	s_addc_u32 s66, s81, 0
	s_mov_b32 s68, -2
	ds_read_b128 v[112:115], v218
	ds_read_b128 v[116:119], v218 offset:1024
	ds_read_b128 v[120:123], v218 offset:2048
	ds_read_b128 v[124:127], v218 offset:3072
	s_waitcnt vmcnt(0)
	ds_read_b128 v[128:131], v219
	ds_read_b128 v[132:135], v219 offset:1024
	ds_read_b128 v[136:139], v219 offset:2048
	ds_read_b128 v[140:143], v219 offset:3072
	s_add_u32 s69, s12, 0xfffc0080
	s_addc_u32 s73, s13, -1
	s_cmp_eq_u32 s68, 12
	s_cselect_b32 s83, s1, s73
	s_cselect_b32 s82, s2, s69
	s_cselect_b32 s81, s3, s66
	s_cselect_b32 s80, s34, s35
	v_lshl_add_u64 v[230:231], s[12:13], 0, v[192:193]
	s_add_i32 m0, s15, 0xc000
	ds_read_b128 v[152:155], v220
	ds_read_b128 v[156:159], v220 offset:1024
	ds_read_b128 v[160:163], v220 offset:2048
	ds_read_b128 v[164:167], v220 offset:3072
	ds_read_b128 v[200:203], v220 offset:4096
	ds_read_b128 v[204:207], v220 offset:5120
	ds_read_b128 v[208:211], v220 offset:6144
	ds_read_b128 v[226:229], v220 offset:7168
	global_load_lds_dwordx4 v[230:231], off
	v_lshl_add_u64 v[230:231], s[12:13], 0, v[194:195]
	s_add_i32 m0, s15, 0xe000
	s_nop 0
	global_load_lds_dwordx4 v[230:231], off
	s_waitcnt vmcnt(8)
	s_waitcnt lgkmcnt(0)
	s_barrier
	s_setprio 1
	s_waitcnt lgkmcnt(0)
	v_mfma_f32_16x16x32_bf16 v[172:175], v[112:115], v[152:155], 0
	v_mfma_f32_16x16x32_bf16 v[172:175], v[116:119], v[156:159], v[172:175]
	v_mfma_f32_16x16x32_bf16 v[168:171], v[120:123], v[152:155], 0
	v_mfma_f32_16x16x32_bf16 v[168:171], v[124:127], v[156:159], v[168:171]
	v_mfma_f32_16x16x32_bf16 v[104:107], v[120:123], v[160:163], 0
	v_mfma_f32_16x16x32_bf16 v[104:107], v[124:127], v[164:167], v[104:107]
	v_mfma_f32_16x16x32_bf16 v[108:111], v[112:115], v[160:163], 0
	v_mfma_f32_16x16x32_bf16 v[108:111], v[116:119], v[164:167], v[108:111]
	v_mfma_f32_16x16x32_bf16 v[92:95], v[112:115], v[200:203], 0
	v_mfma_f32_16x16x32_bf16 v[92:95], v[116:119], v[204:207], v[92:95]
	v_mfma_f32_16x16x32_bf16 v[88:91], v[120:123], v[200:203], 0
	v_mfma_f32_16x16x32_bf16 v[88:91], v[124:127], v[204:207], v[88:91]
	v_mfma_f32_16x16x32_bf16 v[72:75], v[120:123], v[208:211], 0
	v_mfma_f32_16x16x32_bf16 v[72:75], v[124:127], v[226:229], v[72:75]
	v_mfma_f32_16x16x32_bf16 v[76:79], v[112:115], v[208:211], 0
	v_mfma_f32_16x16x32_bf16 v[76:79], v[116:119], v[226:229], v[76:79]
	s_setprio 0
	s_setprio 1
	v_mfma_f32_16x16x32_bf16 v[148:151], v[128:131], v[152:155], 0
	v_mfma_f32_16x16x32_bf16 v[148:151], v[132:135], v[156:159], v[148:151]
	v_mfma_f32_16x16x32_bf16 v[144:147], v[136:139], v[152:155], 0
	v_mfma_f32_16x16x32_bf16 v[144:147], v[140:143], v[156:159], v[144:147]
	v_mfma_f32_16x16x32_bf16 v[96:99], v[136:139], v[160:163], 0
	v_mfma_f32_16x16x32_bf16 v[96:99], v[140:143], v[164:167], v[96:99]
	v_mfma_f32_16x16x32_bf16 v[100:103], v[128:131], v[160:163], 0
	v_mfma_f32_16x16x32_bf16 v[100:103], v[132:135], v[164:167], v[100:103]
	v_mfma_f32_16x16x32_bf16 v[84:87], v[128:131], v[200:203], 0
	v_mfma_f32_16x16x32_bf16 v[84:87], v[132:135], v[204:207], v[84:87]
	v_mfma_f32_16x16x32_bf16 v[80:83], v[136:139], v[200:203], 0
	v_mfma_f32_16x16x32_bf16 v[80:83], v[140:143], v[204:207], v[80:83]
	v_mfma_f32_16x16x32_bf16 v[64:67], v[136:139], v[208:211], 0
	v_mfma_f32_16x16x32_bf16 v[64:67], v[140:143], v[226:229], v[64:67]
	v_mfma_f32_16x16x32_bf16 v[68:71], v[128:131], v[208:211], 0
	v_mfma_f32_16x16x32_bf16 v[68:71], v[132:135], v[226:229], v[68:71]
	s_setprio 0
	s_barrier
	s_add_i32 s69, s59, s14
	v_lshl_add_u64 v[230:231], s[80:81], 0, v[178:179]
	s_mov_b32 m0, s69
	ds_read_b128 v[152:155], v220 offset:16384
	ds_read_b128 v[156:159], v220 offset:17408
	ds_read_b128 v[160:163], v220 offset:18432
	ds_read_b128 v[164:167], v220 offset:19456
	ds_read_b128 v[200:203], v220 offset:20480
	ds_read_b128 v[204:207], v220 offset:21504
	ds_read_b128 v[208:211], v220 offset:22528
	ds_read_b128 v[226:229], v220 offset:23552
	global_load_lds_dwordx4 v[230:231], off
	s_add_i32 m0, s69, 0x2000
	s_add_u32 s86, s80, 0x40000
	v_lshl_add_u64 v[232:233], s[80:81], 0, v[182:183]
	s_addc_u32 s87, s81, 0
	s_add_i32 s69, s65, s14
	global_load_lds_dwordx4 v[232:233], off
	v_lshl_add_u64 v[234:235], s[86:87], 0, v[178:179]
	s_mov_b32 m0, s69
	v_lshl_add_u64 v[236:237], s[82:83], 0, v[180:181]
	global_load_lds_dwordx4 v[234:235], off
	v_lshl_add_u64 v[234:235], s[86:87], 0, v[182:183]
	s_add_i32 m0, s69, 0x2000
	s_nop 0
	global_load_lds_dwordx4 v[234:235], off
	v_lshl_add_u64 v[234:235], s[82:83], 0, v[176:177]
	s_mov_b32 m0, s15
	s_nop 0
	global_load_lds_dwordx4 v[234:235], off
	s_mov_b32 m0, s52
	s_nop 0
	global_load_lds_dwordx4 v[236:237], off
	s_waitcnt vmcnt(8)
	s_waitcnt lgkmcnt(0)
	s_barrier
	s_setprio 1
	s_waitcnt lgkmcnt(0)
	v_mfma_f32_16x16x32_bf16 v[60:63], v[112:115], v[152:155], 0
	v_mfma_f32_16x16x32_bf16 v[60:63], v[116:119], v[156:159], v[60:63]
	v_mfma_f32_16x16x32_bf16 v[56:59], v[120:123], v[152:155], 0
	v_mfma_f32_16x16x32_bf16 v[56:59], v[124:127], v[156:159], v[56:59]
	v_mfma_f32_16x16x32_bf16 v[40:43], v[120:123], v[160:163], 0
	v_mfma_f32_16x16x32_bf16 v[40:43], v[124:127], v[164:167], v[40:43]
	v_mfma_f32_16x16x32_bf16 v[44:47], v[112:115], v[160:163], 0
	v_mfma_f32_16x16x32_bf16 v[44:47], v[116:119], v[164:167], v[44:47]
	v_mfma_f32_16x16x32_bf16 v[28:31], v[112:115], v[200:203], 0
	v_mfma_f32_16x16x32_bf16 v[28:31], v[116:119], v[204:207], v[28:31]
	v_mfma_f32_16x16x32_bf16 v[24:27], v[120:123], v[200:203], 0
	v_mfma_f32_16x16x32_bf16 v[24:27], v[124:127], v[204:207], v[24:27]
	v_mfma_f32_16x16x32_bf16 v[8:11], v[120:123], v[208:211], 0
	v_mfma_f32_16x16x32_bf16 v[8:11], v[124:127], v[226:229], v[8:11]
	v_mfma_f32_16x16x32_bf16 v[12:15], v[112:115], v[208:211], 0
	v_mfma_f32_16x16x32_bf16 v[12:15], v[116:119], v[226:229], v[12:15]
	s_setprio 0
	s_setprio 1
	v_mfma_f32_16x16x32_bf16 v[52:55], v[128:131], v[152:155], 0
	v_mfma_f32_16x16x32_bf16 v[52:55], v[132:135], v[156:159], v[52:55]
	v_mfma_f32_16x16x32_bf16 v[48:51], v[136:139], v[152:155], 0
	v_mfma_f32_16x16x32_bf16 v[48:51], v[140:143], v[156:159], v[48:51]
	v_mfma_f32_16x16x32_bf16 v[32:35], v[136:139], v[160:163], 0
	v_mfma_f32_16x16x32_bf16 v[32:35], v[140:143], v[164:167], v[32:35]
	v_mfma_f32_16x16x32_bf16 v[36:39], v[128:131], v[160:163], 0
	v_mfma_f32_16x16x32_bf16 v[36:39], v[132:135], v[164:167], v[36:39]
	v_mfma_f32_16x16x32_bf16 v[20:23], v[128:131], v[200:203], 0
	v_mfma_f32_16x16x32_bf16 v[20:23], v[132:135], v[204:207], v[20:23]
	v_mfma_f32_16x16x32_bf16 v[16:19], v[136:139], v[200:203], 0
	v_mfma_f32_16x16x32_bf16 v[16:19], v[140:143], v[204:207], v[16:19]
	v_mfma_f32_16x16x32_bf16 v[0:3], v[136:139], v[208:211], 0
	v_mfma_f32_16x16x32_bf16 v[0:3], v[140:143], v[226:229], v[0:3]
	v_mfma_f32_16x16x32_bf16 v[4:7], v[128:131], v[208:211], 0
	v_mfma_f32_16x16x32_bf16 v[4:7], v[132:135], v[226:229], v[4:7]
	s_setprio 0
	s_barrier
	s_add_i32 s69, 0, 0x18000
	s_add_i32 s73, 0, 0x1c000
	v_add_u32_e32 v124, s69, v212
	v_add_u32_e32 v140, s73, v212
	ds_read_b128 v[112:115], v124
	ds_read_b128 v[116:119], v124 offset:1024
	ds_read_b128 v[120:123], v124 offset:2048
	ds_read_b128 v[124:127], v124 offset:3072
	ds_read_b128 v[128:131], v140
	ds_read_b128 v[132:135], v140 offset:1024
	ds_read_b128 v[136:139], v140 offset:2048
	ds_read_b128 v[140:143], v140 offset:3072
	s_add_u32 s82, s82, 0x40000
	s_addc_u32 s83, s83, 0
	s_mov_b32 m0, s53
	v_lshl_add_u64 v[238:239], s[82:83], 0, v[176:177]
	ds_read_b128 v[152:155], v220 offset:32768
	ds_read_b128 v[156:159], v220 offset:33792
	ds_read_b128 v[160:163], v220 offset:34816
	ds_read_b128 v[164:167], v220 offset:35840
	ds_read_b128 v[200:203], v220 offset:36864
	ds_read_b128 v[204:207], v220 offset:37888
	ds_read_b128 v[208:211], v220 offset:38912
	ds_read_b128 v[226:229], v220 offset:39936
	global_load_lds_dwordx4 v[238:239], off
	v_lshl_add_u64 v[238:239], s[82:83], 0, v[180:181]
	s_mov_b32 m0, s54
	s_nop 0
	global_load_lds_dwordx4 v[238:239], off
	s_waitcnt vmcnt(8)
	s_waitcnt lgkmcnt(0)
	s_barrier
	s_setprio 1
	s_waitcnt lgkmcnt(0)
	v_mfma_f32_16x16x32_bf16 v[172:175], v[112:115], v[152:155], v[172:175]
	v_mfma_f32_16x16x32_bf16 v[172:175], v[116:119], v[156:159], v[172:175]
	v_mfma_f32_16x16x32_bf16 v[168:171], v[120:123], v[152:155], v[168:171]
	v_mfma_f32_16x16x32_bf16 v[168:171], v[124:127], v[156:159], v[168:171]
	v_mfma_f32_16x16x32_bf16 v[104:107], v[120:123], v[160:163], v[104:107]
	v_mfma_f32_16x16x32_bf16 v[104:107], v[124:127], v[164:167], v[104:107]
	v_mfma_f32_16x16x32_bf16 v[108:111], v[112:115], v[160:163], v[108:111]
	v_mfma_f32_16x16x32_bf16 v[108:111], v[116:119], v[164:167], v[108:111]
	v_mfma_f32_16x16x32_bf16 v[92:95], v[112:115], v[200:203], v[92:95]
	v_mfma_f32_16x16x32_bf16 v[92:95], v[116:119], v[204:207], v[92:95]
	v_mfma_f32_16x16x32_bf16 v[88:91], v[120:123], v[200:203], v[88:91]
	v_mfma_f32_16x16x32_bf16 v[88:91], v[124:127], v[204:207], v[88:91]
	v_mfma_f32_16x16x32_bf16 v[72:75], v[120:123], v[208:211], v[72:75]
	v_mfma_f32_16x16x32_bf16 v[72:75], v[124:127], v[226:229], v[72:75]
	v_mfma_f32_16x16x32_bf16 v[76:79], v[112:115], v[208:211], v[76:79]
	v_mfma_f32_16x16x32_bf16 v[76:79], v[116:119], v[226:229], v[76:79]
	s_setprio 0
	s_setprio 1
	v_mfma_f32_16x16x32_bf16 v[148:151], v[128:131], v[152:155], v[148:151]
	v_mfma_f32_16x16x32_bf16 v[148:151], v[132:135], v[156:159], v[148:151]
	v_mfma_f32_16x16x32_bf16 v[144:147], v[136:139], v[152:155], v[144:147]
	v_mfma_f32_16x16x32_bf16 v[144:147], v[140:143], v[156:159], v[144:147]
	v_mfma_f32_16x16x32_bf16 v[96:99], v[136:139], v[160:163], v[96:99]
	v_mfma_f32_16x16x32_bf16 v[96:99], v[140:143], v[164:167], v[96:99]
	v_mfma_f32_16x16x32_bf16 v[100:103], v[128:131], v[160:163], v[100:103]
	v_mfma_f32_16x16x32_bf16 v[100:103], v[132:135], v[164:167], v[100:103]
	v_mfma_f32_16x16x32_bf16 v[84:87], v[128:131], v[200:203], v[84:87]
	v_mfma_f32_16x16x32_bf16 v[84:87], v[132:135], v[204:207], v[84:87]
	v_mfma_f32_16x16x32_bf16 v[80:83], v[136:139], v[200:203], v[80:83]
	v_mfma_f32_16x16x32_bf16 v[80:83], v[140:143], v[204:207], v[80:83]
	v_mfma_f32_16x16x32_bf16 v[64:67], v[136:139], v[208:211], v[64:67]
	v_mfma_f32_16x16x32_bf16 v[64:67], v[140:143], v[226:229], v[64:67]
	v_mfma_f32_16x16x32_bf16 v[68:71], v[128:131], v[208:211], v[68:71]
	v_mfma_f32_16x16x32_bf16 v[68:71], v[132:135], v[226:229], v[68:71]
	s_setprio 0
	s_barrier
	s_add_i32 s69, s69, s14
	v_lshl_add_u64 v[230:231], v[230:231], 0, s[40:41]
	s_mov_b32 m0, s69
	ds_read_b128 v[152:155], v220 offset:49152
	ds_read_b128 v[156:159], v220 offset:50176
	ds_read_b128 v[160:163], v220 offset:51200
	ds_read_b128 v[164:167], v220 offset:52224
	ds_read_b128 v[200:203], v220 offset:53248
	ds_read_b128 v[204:207], v220 offset:54272
	ds_read_b128 v[208:211], v220 offset:55296
	ds_read_b128 v[226:229], v220 offset:56320
	global_load_lds_dwordx4 v[230:231], off
	s_add_i32 m0, s69, 0x2000
	s_add_u32 s80, s80, 0x40080
	v_lshl_add_u64 v[230:231], v[232:233], 0, s[40:41]
	s_addc_u32 s81, s81, 0
	s_add_i32 s69, s73, s14
	global_load_lds_dwordx4 v[230:231], off
	v_lshl_add_u64 v[230:231], s[80:81], 0, v[178:179]
	s_mov_b32 m0, s69
	s_nop 0
	global_load_lds_dwordx4 v[230:231], off
	v_lshl_add_u64 v[230:231], s[80:81], 0, v[182:183]
	s_add_i32 m0, s69, 0x2000
	s_nop 0
	global_load_lds_dwordx4 v[230:231], off
	v_lshl_add_u64 v[230:231], v[234:235], 0, s[40:41]
	s_mov_b32 m0, s57
	s_nop 0
	global_load_lds_dwordx4 v[230:231], off
	v_lshl_add_u64 v[230:231], v[236:237], 0, s[40:41]
	s_mov_b32 m0, s58
	s_nop 0
	global_load_lds_dwordx4 v[230:231], off
	s_waitcnt vmcnt(8)
	s_waitcnt lgkmcnt(0)
	s_barrier
	s_setprio 1
	s_waitcnt lgkmcnt(0)
	v_mfma_f32_16x16x32_bf16 v[60:63], v[112:115], v[152:155], v[60:63]
	v_mfma_f32_16x16x32_bf16 v[60:63], v[116:119], v[156:159], v[60:63]
	v_mfma_f32_16x16x32_bf16 v[56:59], v[120:123], v[152:155], v[56:59]
	v_mfma_f32_16x16x32_bf16 v[56:59], v[124:127], v[156:159], v[56:59]
	v_mfma_f32_16x16x32_bf16 v[40:43], v[120:123], v[160:163], v[40:43]
	v_mfma_f32_16x16x32_bf16 v[40:43], v[124:127], v[164:167], v[40:43]
	v_mfma_f32_16x16x32_bf16 v[44:47], v[112:115], v[160:163], v[44:47]
	v_mfma_f32_16x16x32_bf16 v[44:47], v[116:119], v[164:167], v[44:47]
	v_mfma_f32_16x16x32_bf16 v[28:31], v[112:115], v[200:203], v[28:31]
	v_mfma_f32_16x16x32_bf16 v[28:31], v[116:119], v[204:207], v[28:31]
	v_mfma_f32_16x16x32_bf16 v[24:27], v[120:123], v[200:203], v[24:27]
	v_mfma_f32_16x16x32_bf16 v[24:27], v[124:127], v[204:207], v[24:27]
	v_mfma_f32_16x16x32_bf16 v[8:11], v[120:123], v[208:211], v[8:11]
	v_mfma_f32_16x16x32_bf16 v[8:11], v[124:127], v[226:229], v[8:11]
	v_mfma_f32_16x16x32_bf16 v[12:15], v[112:115], v[208:211], v[12:15]
	v_mfma_f32_16x16x32_bf16 v[12:15], v[116:119], v[226:229], v[12:15]
	s_setprio 0
	s_setprio 1
	v_mfma_f32_16x16x32_bf16 v[52:55], v[128:131], v[152:155], v[52:55]
	v_mfma_f32_16x16x32_bf16 v[52:55], v[132:135], v[156:159], v[52:55]
	v_mfma_f32_16x16x32_bf16 v[48:51], v[136:139], v[152:155], v[48:51]
	v_mfma_f32_16x16x32_bf16 v[48:51], v[140:143], v[156:159], v[48:51]
	v_mfma_f32_16x16x32_bf16 v[32:35], v[136:139], v[160:163], v[32:35]
	v_mfma_f32_16x16x32_bf16 v[32:35], v[140:143], v[164:167], v[32:35]
	v_mfma_f32_16x16x32_bf16 v[36:39], v[128:131], v[160:163], v[36:39]
	v_mfma_f32_16x16x32_bf16 v[36:39], v[132:135], v[164:167], v[36:39]
	v_mfma_f32_16x16x32_bf16 v[20:23], v[128:131], v[200:203], v[20:23]
	v_mfma_f32_16x16x32_bf16 v[20:23], v[132:135], v[204:207], v[20:23]
	v_mfma_f32_16x16x32_bf16 v[16:19], v[136:139], v[200:203], v[16:19]
	v_mfma_f32_16x16x32_bf16 v[16:19], v[140:143], v[204:207], v[16:19]
	v_mfma_f32_16x16x32_bf16 v[0:3], v[136:139], v[208:211], v[0:3]
	v_mfma_f32_16x16x32_bf16 v[0:3], v[140:143], v[226:229], v[0:3]
	v_mfma_f32_16x16x32_bf16 v[4:7], v[128:131], v[208:211], v[4:7]
	v_mfma_f32_16x16x32_bf16 v[4:7], v[132:135], v[226:229], v[4:7]
	s_setprio 0
	s_barrier
	s_add_i32 s68, s68, 2
	s_add_u32 s12, s12, 0x100
	s_addc_u32 s13, s13, 0
	s_add_u32 s35, s35, 0x100
	s_addc_u32 s66, s66, 0

.LBB0_645:
	s_ashr_i32 s31, s30, 31
	s_lshl_b64 s[36:37], s[30:31], 19
	s_add_u32 s36, s92, s36
	s_addc_u32 s37, s93, s37
	s_and_b64 s[38:39], s[8:9], exec
	s_cselect_b32 s31, s37, s43
	s_cselect_b32 s41, s36, s42
	s_ashr_i32 s29, s28, 31
	s_lshl_b64 s[38:39], s[28:29], 19
	s_add_u32 s38, s10, s38
	s_addc_u32 s39, s11, s39
	s_and_b64 s[46:47], s[8:9], exec
	s_cselect_b32 s29, s39, s45
	s_cselect_b32 s54, s38, s44
	s_add_u32 s42, s42, 0x40080
	s_addc_u32 s43, s43, 0
	s_add_u32 s55, s44, 0x100
	s_addc_u32 s56, s45, 0
	s_mov_b32 s57, -2
	s_waitcnt lgkmcnt(0)
	ds_read_b128 v[88:91], v236
	ds_read_b128 v[100:103], v236 offset:1024
	ds_read_b128 v[112:115], v236 offset:2048
	ds_read_b128 v[124:127], v236 offset:3072
	ds_read_b128 v[136:139], v237
	ds_read_b128 v[148:151], v237 offset:1024
	ds_read_b128 v[152:155], v237 offset:2048
	ds_read_b128 v[156:159], v237 offset:3072
	s_add_u32 s44, s42, 0xfffc0080
	s_addc_u32 s45, s43, -1
	s_cmp_eq_u32 s57, 12
	s_cselect_b32 s47, s31, s45
	s_cselect_b32 s46, s41, s44
	s_cselect_b32 s45, s29, s56
	s_cselect_b32 s44, s54, s55
	v_lshl_add_u64 v[208:209], s[42:43], 0, v[194:195]
	s_add_i32 m0, s3, 0xc000
	ds_read_b128 v[160:163], v238
	ds_read_b128 v[164:167], v238 offset:1024
	ds_read_b128 v[168:171], v238 offset:2048
	ds_read_b128 v[172:175], v238 offset:3072
	ds_read_b128 v[176:179], v238 offset:4096
	ds_read_b128 v[180:183], v238 offset:5120
	ds_read_b128 v[202:205], v238 offset:6144
	ds_read_b128 v[228:231], v238 offset:7168
	global_load_lds_dwordx4 v[208:209], off
	v_lshl_add_u64 v[208:209], s[42:43], 0, v[196:197]
	s_add_i32 m0, s3, 0xe000
	s_nop 0
	global_load_lds_dwordx4 v[208:209], off
	s_waitcnt vmcnt(8)
	s_waitcnt lgkmcnt(0)
	s_barrier
	s_setprio 1
	s_waitcnt lgkmcnt(0)
	v_mfma_f32_16x16x32_bf16 v[144:147], v[88:91], v[160:163], 0
	v_mfma_f32_16x16x32_bf16 v[144:147], v[100:103], v[164:167], v[144:147]
	v_mfma_f32_16x16x32_bf16 v[140:143], v[112:115], v[160:163], 0
	v_mfma_f32_16x16x32_bf16 v[140:143], v[124:127], v[164:167], v[140:143]
	v_mfma_f32_16x16x32_bf16 v[116:119], v[112:115], v[168:171], 0
	v_mfma_f32_16x16x32_bf16 v[116:119], v[124:127], v[172:175], v[116:119]
	v_mfma_f32_16x16x32_bf16 v[120:123], v[88:91], v[168:171], 0
	v_mfma_f32_16x16x32_bf16 v[120:123], v[100:103], v[172:175], v[120:123]
	v_mfma_f32_16x16x32_bf16 v[96:99], v[88:91], v[176:179], 0
	v_mfma_f32_16x16x32_bf16 v[96:99], v[100:103], v[180:183], v[96:99]
	v_mfma_f32_16x16x32_bf16 v[92:95], v[112:115], v[176:179], 0
	v_mfma_f32_16x16x32_bf16 v[92:95], v[124:127], v[180:183], v[92:95]
	v_mfma_f32_16x16x32_bf16 v[72:75], v[112:115], v[202:205], 0
	v_mfma_f32_16x16x32_bf16 v[72:75], v[124:127], v[228:231], v[72:75]
	v_mfma_f32_16x16x32_bf16 v[76:79], v[88:91], v[202:205], 0
	v_mfma_f32_16x16x32_bf16 v[76:79], v[100:103], v[228:231], v[76:79]
	s_setprio 0
	s_setprio 1
	v_mfma_f32_16x16x32_bf16 v[132:135], v[136:139], v[160:163], 0
	v_mfma_f32_16x16x32_bf16 v[132:135], v[148:151], v[164:167], v[132:135]
	v_mfma_f32_16x16x32_bf16 v[128:131], v[152:155], v[160:163], 0
	v_mfma_f32_16x16x32_bf16 v[128:131], v[156:159], v[164:167], v[128:131]
	v_mfma_f32_16x16x32_bf16 v[104:107], v[152:155], v[168:171], 0
	v_mfma_f32_16x16x32_bf16 v[104:107], v[156:159], v[172:175], v[104:107]
	v_mfma_f32_16x16x32_bf16 v[108:111], v[136:139], v[168:171], 0
	v_mfma_f32_16x16x32_bf16 v[108:111], v[148:151], v[172:175], v[108:111]
	v_mfma_f32_16x16x32_bf16 v[84:87], v[136:139], v[176:179], 0
	v_mfma_f32_16x16x32_bf16 v[84:87], v[148:151], v[180:183], v[84:87]
	v_mfma_f32_16x16x32_bf16 v[80:83], v[152:155], v[176:179], 0
	v_mfma_f32_16x16x32_bf16 v[80:83], v[156:159], v[180:183], v[80:83]
	v_mfma_f32_16x16x32_bf16 v[64:67], v[152:155], v[202:205], 0
	v_mfma_f32_16x16x32_bf16 v[64:67], v[156:159], v[228:231], v[64:67]
	v_mfma_f32_16x16x32_bf16 v[68:71], v[136:139], v[202:205], 0
	v_mfma_f32_16x16x32_bf16 v[68:71], v[148:151], v[228:231], v[68:71]
	s_setprio 0
	s_barrier
	s_add_i32 s58, s51, s2
	v_lshl_add_u64 v[208:209], s[44:45], 0, v[186:187]
	s_mov_b32 m0, s58
	ds_read_b128 v[160:163], v238 offset:16384
	ds_read_b128 v[164:167], v238 offset:17408
	ds_read_b128 v[168:171], v238 offset:18432
	ds_read_b128 v[172:175], v238 offset:19456
	ds_read_b128 v[176:179], v238 offset:20480
	ds_read_b128 v[180:183], v238 offset:21504
	ds_read_b128 v[202:205], v238 offset:22528
	ds_read_b128 v[228:231], v238 offset:23552
	global_load_lds_dwordx4 v[208:209], off
	s_add_i32 m0, s58, 0x2000
	s_add_u32 s58, s44, 0x40000
	v_lshl_add_u64 v[212:213], s[44:45], 0, v[190:191]
	s_addc_u32 s59, s45, 0
	s_add_i32 s64, s52, s2
	global_load_lds_dwordx4 v[212:213], off
	v_lshl_add_u64 v[216:217], s[58:59], 0, v[186:187]
	s_mov_b32 m0, s64
	v_lshl_add_u64 v[220:221], s[46:47], 0, v[188:189]
	global_load_lds_dwordx4 v[216:217], off
	v_lshl_add_u64 v[216:217], s[58:59], 0, v[190:191]
	s_add_i32 m0, s64, 0x2000
	s_nop 0
	global_load_lds_dwordx4 v[216:217], off
	v_lshl_add_u64 v[216:217], s[46:47], 0, v[184:185]
	s_mov_b32 m0, s3
	s_nop 0
	global_load_lds_dwordx4 v[216:217], off
	s_mov_b32 m0, s33
	s_nop 0
	global_load_lds_dwordx4 v[220:221], off
	s_waitcnt vmcnt(8)
	s_waitcnt lgkmcnt(0)
	s_barrier
	s_setprio 1
	s_waitcnt lgkmcnt(0)
	v_mfma_f32_16x16x32_bf16 v[60:63], v[88:91], v[160:163], 0
	v_mfma_f32_16x16x32_bf16 v[60:63], v[100:103], v[164:167], v[60:63]
	v_mfma_f32_16x16x32_bf16 v[56:59], v[112:115], v[160:163], 0
	v_mfma_f32_16x16x32_bf16 v[56:59], v[124:127], v[164:167], v[56:59]
	v_mfma_f32_16x16x32_bf16 v[40:43], v[112:115], v[168:171], 0
	v_mfma_f32_16x16x32_bf16 v[40:43], v[124:127], v[172:175], v[40:43]
	v_mfma_f32_16x16x32_bf16 v[44:47], v[88:91], v[168:171], 0
	v_mfma_f32_16x16x32_bf16 v[44:47], v[100:103], v[172:175], v[44:47]
	v_mfma_f32_16x16x32_bf16 v[28:31], v[88:91], v[176:179], 0
	v_mfma_f32_16x16x32_bf16 v[28:31], v[100:103], v[180:183], v[28:31]
	v_mfma_f32_16x16x32_bf16 v[24:27], v[112:115], v[176:179], 0
	v_mfma_f32_16x16x32_bf16 v[24:27], v[124:127], v[180:183], v[24:27]
	v_mfma_f32_16x16x32_bf16 v[8:11], v[112:115], v[202:205], 0
	v_mfma_f32_16x16x32_bf16 v[8:11], v[124:127], v[228:231], v[8:11]
	v_mfma_f32_16x16x32_bf16 v[12:15], v[88:91], v[202:205], 0
	v_mfma_f32_16x16x32_bf16 v[12:15], v[100:103], v[228:231], v[12:15]
	s_setprio 0
	s_setprio 1
	v_mfma_f32_16x16x32_bf16 v[52:55], v[136:139], v[160:163], 0
	v_mfma_f32_16x16x32_bf16 v[52:55], v[148:151], v[164:167], v[52:55]
	v_mfma_f32_16x16x32_bf16 v[48:51], v[152:155], v[160:163], 0
	v_mfma_f32_16x16x32_bf16 v[48:51], v[156:159], v[164:167], v[48:51]
	v_mfma_f32_16x16x32_bf16 v[32:35], v[152:155], v[168:171], 0
	v_mfma_f32_16x16x32_bf16 v[32:35], v[156:159], v[172:175], v[32:35]
	v_mfma_f32_16x16x32_bf16 v[36:39], v[136:139], v[168:171], 0
	v_mfma_f32_16x16x32_bf16 v[36:39], v[148:151], v[172:175], v[36:39]
	v_mfma_f32_16x16x32_bf16 v[20:23], v[136:139], v[176:179], 0
	v_mfma_f32_16x16x32_bf16 v[20:23], v[148:151], v[180:183], v[20:23]
	v_mfma_f32_16x16x32_bf16 v[16:19], v[152:155], v[176:179], 0
	v_mfma_f32_16x16x32_bf16 v[16:19], v[156:159], v[180:183], v[16:19]
	v_mfma_f32_16x16x32_bf16 v[0:3], v[152:155], v[202:205], 0
	v_mfma_f32_16x16x32_bf16 v[0:3], v[156:159], v[228:231], v[0:3]
	v_mfma_f32_16x16x32_bf16 v[4:7], v[136:139], v[202:205], 0
	v_mfma_f32_16x16x32_bf16 v[4:7], v[148:151], v[228:231], v[4:7]
	s_setprio 0
	s_barrier
	s_add_i32 s58, 0, 0x18000
	s_add_i32 s59, 0, 0x1c000
	v_add_u32_e32 v124, s58, v211
	v_add_u32_e32 v156, s59, v211
	ds_read_b128 v[88:91], v124
	ds_read_b128 v[100:103], v124 offset:1024
	ds_read_b128 v[112:115], v124 offset:2048
	ds_read_b128 v[124:127], v124 offset:3072
	ds_read_b128 v[136:139], v156
	ds_read_b128 v[148:151], v156 offset:1024
	ds_read_b128 v[152:155], v156 offset:2048
	ds_read_b128 v[156:159], v156 offset:3072
	s_add_u32 s46, s46, 0x40000
	s_addc_u32 s47, s47, 0
	s_mov_b32 m0, s34
	v_lshl_add_u64 v[224:225], s[46:47], 0, v[184:185]
	ds_read_b128 v[160:163], v238 offset:32768
	ds_read_b128 v[164:167], v238 offset:33792
	ds_read_b128 v[168:171], v238 offset:34816
	ds_read_b128 v[172:175], v238 offset:35840
	ds_read_b128 v[176:179], v238 offset:36864
	ds_read_b128 v[180:183], v238 offset:37888
	ds_read_b128 v[202:205], v238 offset:38912
	ds_read_b128 v[228:231], v238 offset:39936
	global_load_lds_dwordx4 v[224:225], off
	v_lshl_add_u64 v[224:225], s[46:47], 0, v[188:189]
	s_mov_b32 m0, s35
	s_nop 0
	global_load_lds_dwordx4 v[224:225], off
	s_waitcnt vmcnt(8)
	s_waitcnt lgkmcnt(0)
	s_barrier
	s_setprio 1
	s_waitcnt lgkmcnt(0)
	v_mfma_f32_16x16x32_bf16 v[144:147], v[88:91], v[160:163], v[144:147]
	v_mfma_f32_16x16x32_bf16 v[144:147], v[100:103], v[164:167], v[144:147]
	v_mfma_f32_16x16x32_bf16 v[140:143], v[112:115], v[160:163], v[140:143]
	v_mfma_f32_16x16x32_bf16 v[140:143], v[124:127], v[164:167], v[140:143]
	v_mfma_f32_16x16x32_bf16 v[116:119], v[112:115], v[168:171], v[116:119]
	v_mfma_f32_16x16x32_bf16 v[116:119], v[124:127], v[172:175], v[116:119]
	v_mfma_f32_16x16x32_bf16 v[120:123], v[88:91], v[168:171], v[120:123]
	v_mfma_f32_16x16x32_bf16 v[120:123], v[100:103], v[172:175], v[120:123]
	v_mfma_f32_16x16x32_bf16 v[96:99], v[88:91], v[176:179], v[96:99]
	v_mfma_f32_16x16x32_bf16 v[96:99], v[100:103], v[180:183], v[96:99]
	v_mfma_f32_16x16x32_bf16 v[92:95], v[112:115], v[176:179], v[92:95]
	v_mfma_f32_16x16x32_bf16 v[92:95], v[124:127], v[180:183], v[92:95]
	v_mfma_f32_16x16x32_bf16 v[72:75], v[112:115], v[202:205], v[72:75]
	v_mfma_f32_16x16x32_bf16 v[72:75], v[124:127], v[228:231], v[72:75]
	v_mfma_f32_16x16x32_bf16 v[76:79], v[88:91], v[202:205], v[76:79]
	v_mfma_f32_16x16x32_bf16 v[76:79], v[100:103], v[228:231], v[76:79]
	s_setprio 0
	s_setprio 1
	v_mfma_f32_16x16x32_bf16 v[132:135], v[136:139], v[160:163], v[132:135]
	v_mfma_f32_16x16x32_bf16 v[132:135], v[148:151], v[164:167], v[132:135]
	v_mfma_f32_16x16x32_bf16 v[128:131], v[152:155], v[160:163], v[128:131]
	v_mfma_f32_16x16x32_bf16 v[128:131], v[156:159], v[164:167], v[128:131]
	v_mfma_f32_16x16x32_bf16 v[104:107], v[152:155], v[168:171], v[104:107]
	v_mfma_f32_16x16x32_bf16 v[104:107], v[156:159], v[172:175], v[104:107]
	v_mfma_f32_16x16x32_bf16 v[108:111], v[136:139], v[168:171], v[108:111]
	v_mfma_f32_16x16x32_bf16 v[108:111], v[148:151], v[172:175], v[108:111]
	v_mfma_f32_16x16x32_bf16 v[84:87], v[136:139], v[176:179], v[84:87]
	v_mfma_f32_16x16x32_bf16 v[84:87], v[148:151], v[180:183], v[84:87]
	v_mfma_f32_16x16x32_bf16 v[80:83], v[152:155], v[176:179], v[80:83]
	v_mfma_f32_16x16x32_bf16 v[80:83], v[156:159], v[180:183], v[80:83]
	v_mfma_f32_16x16x32_bf16 v[64:67], v[152:155], v[202:205], v[64:67]
	v_mfma_f32_16x16x32_bf16 v[64:67], v[156:159], v[228:231], v[64:67]
	v_mfma_f32_16x16x32_bf16 v[68:71], v[136:139], v[202:205], v[68:71]
	v_mfma_f32_16x16x32_bf16 v[68:71], v[148:151], v[228:231], v[68:71]
	s_setprio 0
	s_barrier
	s_add_i32 s46, s58, s2
	v_lshl_add_u64 v[208:209], v[208:209], 0, s[24:25]
	s_mov_b32 m0, s46
	ds_read_b128 v[160:163], v238 offset:49152
	ds_read_b128 v[164:167], v238 offset:50176
	ds_read_b128 v[168:171], v238 offset:51200
	ds_read_b128 v[172:175], v238 offset:52224
	ds_read_b128 v[176:179], v238 offset:53248
	ds_read_b128 v[180:183], v238 offset:54272
	ds_read_b128 v[202:205], v238 offset:55296
	ds_read_b128 v[228:231], v238 offset:56320
	global_load_lds_dwordx4 v[208:209], off
	s_add_i32 m0, s46, 0x2000
	s_add_u32 s44, s44, 0x40080
	v_lshl_add_u64 v[208:209], v[212:213], 0, s[24:25]
	s_addc_u32 s45, s45, 0
	s_add_i32 s46, s59, s2
	global_load_lds_dwordx4 v[208:209], off
	v_lshl_add_u64 v[208:209], s[44:45], 0, v[186:187]
	s_mov_b32 m0, s46
	s_nop 0
	global_load_lds_dwordx4 v[208:209], off
	v_lshl_add_u64 v[208:209], s[44:45], 0, v[190:191]
	s_add_i32 m0, s46, 0x2000
	s_nop 0
	global_load_lds_dwordx4 v[208:209], off
	v_lshl_add_u64 v[208:209], v[216:217], 0, s[24:25]
	s_mov_b32 m0, s49
	s_nop 0
	global_load_lds_dwordx4 v[208:209], off
	v_lshl_add_u64 v[208:209], v[220:221], 0, s[24:25]
	s_mov_b32 m0, s50
	s_nop 0
	global_load_lds_dwordx4 v[208:209], off
	s_waitcnt vmcnt(8)
	s_waitcnt lgkmcnt(0)
	s_barrier
	s_setprio 1
	s_waitcnt lgkmcnt(0)
	v_mfma_f32_16x16x32_bf16 v[60:63], v[88:91], v[160:163], v[60:63]
	v_mfma_f32_16x16x32_bf16 v[60:63], v[100:103], v[164:167], v[60:63]
	v_mfma_f32_16x16x32_bf16 v[56:59], v[112:115], v[160:163], v[56:59]
	v_mfma_f32_16x16x32_bf16 v[56:59], v[124:127], v[164:167], v[56:59]
	v_mfma_f32_16x16x32_bf16 v[40:43], v[112:115], v[168:171], v[40:43]
	v_mfma_f32_16x16x32_bf16 v[40:43], v[124:127], v[172:175], v[40:43]
	v_mfma_f32_16x16x32_bf16 v[44:47], v[88:91], v[168:171], v[44:47]
	v_mfma_f32_16x16x32_bf16 v[44:47], v[100:103], v[172:175], v[44:47]
	v_mfma_f32_16x16x32_bf16 v[28:31], v[88:91], v[176:179], v[28:31]
	v_mfma_f32_16x16x32_bf16 v[28:31], v[100:103], v[180:183], v[28:31]
	v_mfma_f32_16x16x32_bf16 v[24:27], v[112:115], v[176:179], v[24:27]
	v_mfma_f32_16x16x32_bf16 v[24:27], v[124:127], v[180:183], v[24:27]
	v_mfma_f32_16x16x32_bf16 v[8:11], v[112:115], v[202:205], v[8:11]
	v_mfma_f32_16x16x32_bf16 v[8:11], v[124:127], v[228:231], v[8:11]
	v_mfma_f32_16x16x32_bf16 v[12:15], v[88:91], v[202:205], v[12:15]
	v_mfma_f32_16x16x32_bf16 v[12:15], v[100:103], v[228:231], v[12:15]
	s_setprio 0
	s_setprio 1
	v_mfma_f32_16x16x32_bf16 v[52:55], v[136:139], v[160:163], v[52:55]
	v_mfma_f32_16x16x32_bf16 v[52:55], v[148:151], v[164:167], v[52:55]
	v_mfma_f32_16x16x32_bf16 v[48:51], v[152:155], v[160:163], v[48:51]
	v_mfma_f32_16x16x32_bf16 v[48:51], v[156:159], v[164:167], v[48:51]
	v_mfma_f32_16x16x32_bf16 v[32:35], v[152:155], v[168:171], v[32:35]
	v_mfma_f32_16x16x32_bf16 v[32:35], v[156:159], v[172:175], v[32:35]
	v_mfma_f32_16x16x32_bf16 v[36:39], v[136:139], v[168:171], v[36:39]
	v_mfma_f32_16x16x32_bf16 v[36:39], v[148:151], v[172:175], v[36:39]
	v_mfma_f32_16x16x32_bf16 v[20:23], v[136:139], v[176:179], v[20:23]
	v_mfma_f32_16x16x32_bf16 v[20:23], v[148:151], v[180:183], v[20:23]
	v_mfma_f32_16x16x32_bf16 v[16:19], v[152:155], v[176:179], v[16:19]
	v_mfma_f32_16x16x32_bf16 v[16:19], v[156:159], v[180:183], v[16:19]
	v_mfma_f32_16x16x32_bf16 v[0:3], v[152:155], v[202:205], v[0:3]
	v_mfma_f32_16x16x32_bf16 v[0:3], v[156:159], v[228:231], v[0:3]
	v_mfma_f32_16x16x32_bf16 v[4:7], v[136:139], v[202:205], v[4:7]
	v_mfma_f32_16x16x32_bf16 v[4:7], v[148:151], v[228:231], v[4:7]
	s_setprio 0
	s_barrier
	s_add_i32 s57, s57, 2
	s_add_u32 s42, s42, 0x100
	s_addc_u32 s43, s43, 0
	s_add_u32 s55, s55, 0x100
	s_addc_u32 s56, s56, 0

.LBB0_750:
	s_ashr_i32 s25, s24, 31
	s_lshl_b64 s[26:27], s[24:25], 19
	s_add_u32 s26, s14, s26
	s_addc_u32 s27, s15, s27
	s_and_b64 s[28:29], s[6:7], exec
	s_cselect_b32 s25, s27, s37
	s_cselect_b32 s50, s26, s36
	s_ashr_i32 s23, s22, 31
	s_lshl_b64 s[28:29], s[22:23], 19
	s_add_u32 s28, s16, s28
	s_addc_u32 s29, s17, s29
	s_and_b64 s[40:41], s[6:7], exec
	s_cselect_b32 s23, s29, s39
	s_cselect_b32 s51, s28, s38
	s_add_u32 s36, s36, 0x40080
	s_addc_u32 s37, s37, 0
	s_add_u32 s52, s38, 0x100
	s_addc_u32 s53, s39, 0
	s_mov_b32 s54, -2
	ds_read_b128 v[156:159], v152
	ds_read_b128 v[160:163], v152 offset:1024
	ds_read_b128 v[164:167], v152 offset:2048
	ds_read_b128 v[168:171], v152 offset:3072
	ds_read_b128 v[172:175], v153
	ds_read_b128 v[176:179], v153 offset:1024
	ds_read_b128 v[180:183], v153 offset:2048
	ds_read_b128 v[184:187], v153 offset:3072
	s_add_u32 s38, s36, 0xfffc0080
	s_addc_u32 s39, s37, -1
	s_cmp_eq_u32 s54, 12
	s_cselect_b32 s41, s25, s39
	s_cselect_b32 s40, s50, s38
	s_cselect_b32 s39, s23, s53
	s_cselect_b32 s38, s51, s52
	v_lshl_add_u64 v[146:147], s[36:37], 0, v[138:139]
	s_add_i32 m0, s31, 0xc000
	ds_read_b128 v[188:191], v154
	ds_read_b128 v[192:195], v154 offset:1024
	ds_read_b128 v[196:199], v154 offset:2048
	ds_read_b128 v[200:203], v154 offset:3072
	ds_read_b128 v[204:207], v154 offset:4096
	ds_read_b128 v[208:211], v154 offset:5120
	ds_read_b128 v[216:219], v154 offset:6144
	ds_read_b128 v[220:223], v154 offset:7168
	global_load_lds_dwordx4 v[146:147], off
	v_lshl_add_u64 v[146:147], s[36:37], 0, v[140:141]
	s_add_i32 m0, s31, 0xe000
	s_nop 0
	global_load_lds_dwordx4 v[146:147], off
	s_waitcnt vmcnt(8)
	s_waitcnt lgkmcnt(0)
	s_barrier
	s_setprio 1
	s_waitcnt lgkmcnt(0)
	v_mfma_f32_16x16x32_bf16 v[124:127], v[156:159], v[188:191], 0
	v_mfma_f32_16x16x32_bf16 v[124:127], v[160:163], v[192:195], v[124:127]
	v_mfma_f32_16x16x32_bf16 v[120:123], v[164:167], v[188:191], 0
	v_mfma_f32_16x16x32_bf16 v[120:123], v[168:171], v[192:195], v[120:123]
	v_mfma_f32_16x16x32_bf16 v[104:107], v[164:167], v[196:199], 0
	v_mfma_f32_16x16x32_bf16 v[104:107], v[168:171], v[200:203], v[104:107]
	v_mfma_f32_16x16x32_bf16 v[108:111], v[156:159], v[196:199], 0
	v_mfma_f32_16x16x32_bf16 v[108:111], v[160:163], v[200:203], v[108:111]
	v_mfma_f32_16x16x32_bf16 v[92:95], v[156:159], v[204:207], 0
	v_mfma_f32_16x16x32_bf16 v[92:95], v[160:163], v[208:211], v[92:95]
	v_mfma_f32_16x16x32_bf16 v[88:91], v[164:167], v[204:207], 0
	v_mfma_f32_16x16x32_bf16 v[88:91], v[168:171], v[208:211], v[88:91]
	v_mfma_f32_16x16x32_bf16 v[72:75], v[164:167], v[216:219], 0
	v_mfma_f32_16x16x32_bf16 v[72:75], v[168:171], v[220:223], v[72:75]
	v_mfma_f32_16x16x32_bf16 v[76:79], v[156:159], v[216:219], 0
	v_mfma_f32_16x16x32_bf16 v[76:79], v[160:163], v[220:223], v[76:79]
	s_setprio 0
	s_setprio 1
	v_mfma_f32_16x16x32_bf16 v[116:119], v[172:175], v[188:191], 0
	v_mfma_f32_16x16x32_bf16 v[116:119], v[176:179], v[192:195], v[116:119]
	v_mfma_f32_16x16x32_bf16 v[112:115], v[180:183], v[188:191], 0
	v_mfma_f32_16x16x32_bf16 v[112:115], v[184:187], v[192:195], v[112:115]
	v_mfma_f32_16x16x32_bf16 v[96:99], v[180:183], v[196:199], 0
	v_mfma_f32_16x16x32_bf16 v[96:99], v[184:187], v[200:203], v[96:99]
	v_mfma_f32_16x16x32_bf16 v[100:103], v[172:175], v[196:199], 0
	v_mfma_f32_16x16x32_bf16 v[100:103], v[176:179], v[200:203], v[100:103]
	v_mfma_f32_16x16x32_bf16 v[84:87], v[172:175], v[204:207], 0
	v_mfma_f32_16x16x32_bf16 v[84:87], v[176:179], v[208:211], v[84:87]
	v_mfma_f32_16x16x32_bf16 v[80:83], v[180:183], v[204:207], 0
	v_mfma_f32_16x16x32_bf16 v[80:83], v[184:187], v[208:211], v[80:83]
	v_mfma_f32_16x16x32_bf16 v[64:67], v[180:183], v[216:219], 0
	v_mfma_f32_16x16x32_bf16 v[64:67], v[184:187], v[220:223], v[64:67]
	v_mfma_f32_16x16x32_bf16 v[68:71], v[172:175], v[216:219], 0
	v_mfma_f32_16x16x32_bf16 v[68:71], v[176:179], v[220:223], v[68:71]
	s_setprio 0
	s_barrier
	s_add_i32 s55, s47, s33
	v_lshl_add_u64 v[146:147], s[38:39], 0, v[132:133]
	s_mov_b32 m0, s55
	ds_read_b128 v[188:191], v154 offset:16384
	ds_read_b128 v[192:195], v154 offset:17408
	ds_read_b128 v[196:199], v154 offset:18432
	ds_read_b128 v[200:203], v154 offset:19456
	ds_read_b128 v[204:207], v154 offset:20480
	ds_read_b128 v[208:211], v154 offset:21504
	ds_read_b128 v[216:219], v154 offset:22528
	ds_read_b128 v[220:223], v154 offset:23552
	global_load_lds_dwordx4 v[146:147], off
	s_add_i32 m0, s55, 0x2000
	s_add_u32 s56, s38, 0x40000
	v_lshl_add_u64 v[212:213], s[38:39], 0, v[128:129]
	s_addc_u32 s57, s39, 0
	s_add_i32 s55, s48, s33
	global_load_lds_dwordx4 v[212:213], off
	v_lshl_add_u64 v[224:225], s[56:57], 0, v[132:133]
	s_mov_b32 m0, s55
	v_lshl_add_u64 v[226:227], s[40:41], 0, v[130:131]
	global_load_lds_dwordx4 v[224:225], off
	v_lshl_add_u64 v[224:225], s[56:57], 0, v[128:129]
	s_add_i32 m0, s55, 0x2000
	s_nop 0
	global_load_lds_dwordx4 v[224:225], off
	v_lshl_add_u64 v[224:225], s[40:41], 0, v[134:135]
	s_mov_b32 m0, s31
	s_nop 0
	global_load_lds_dwordx4 v[224:225], off
	s_mov_b32 m0, s34
	s_nop 0
	global_load_lds_dwordx4 v[226:227], off
	s_waitcnt vmcnt(8)
	s_waitcnt lgkmcnt(0)
	s_barrier
	s_setprio 1
	s_waitcnt lgkmcnt(0)
	v_mfma_f32_16x16x32_bf16 v[60:63], v[156:159], v[188:191], 0
	v_mfma_f32_16x16x32_bf16 v[60:63], v[160:163], v[192:195], v[60:63]
	v_mfma_f32_16x16x32_bf16 v[56:59], v[164:167], v[188:191], 0
	v_mfma_f32_16x16x32_bf16 v[56:59], v[168:171], v[192:195], v[56:59]
	v_mfma_f32_16x16x32_bf16 v[40:43], v[164:167], v[196:199], 0
	v_mfma_f32_16x16x32_bf16 v[40:43], v[168:171], v[200:203], v[40:43]
	v_mfma_f32_16x16x32_bf16 v[44:47], v[156:159], v[196:199], 0
	v_mfma_f32_16x16x32_bf16 v[44:47], v[160:163], v[200:203], v[44:47]
	v_mfma_f32_16x16x32_bf16 v[28:31], v[156:159], v[204:207], 0
	v_mfma_f32_16x16x32_bf16 v[28:31], v[160:163], v[208:211], v[28:31]
	v_mfma_f32_16x16x32_bf16 v[24:27], v[164:167], v[204:207], 0
	v_mfma_f32_16x16x32_bf16 v[24:27], v[168:171], v[208:211], v[24:27]
	v_mfma_f32_16x16x32_bf16 v[8:11], v[164:167], v[216:219], 0
	v_mfma_f32_16x16x32_bf16 v[8:11], v[168:171], v[220:223], v[8:11]
	v_mfma_f32_16x16x32_bf16 v[12:15], v[156:159], v[216:219], 0
	v_mfma_f32_16x16x32_bf16 v[12:15], v[160:163], v[220:223], v[12:15]
	s_setprio 0
	s_setprio 1
	v_mfma_f32_16x16x32_bf16 v[52:55], v[172:175], v[188:191], 0
	v_mfma_f32_16x16x32_bf16 v[52:55], v[176:179], v[192:195], v[52:55]
	v_mfma_f32_16x16x32_bf16 v[48:51], v[180:183], v[188:191], 0
	v_mfma_f32_16x16x32_bf16 v[48:51], v[184:187], v[192:195], v[48:51]
	v_mfma_f32_16x16x32_bf16 v[32:35], v[180:183], v[196:199], 0
	v_mfma_f32_16x16x32_bf16 v[32:35], v[184:187], v[200:203], v[32:35]
	v_mfma_f32_16x16x32_bf16 v[36:39], v[172:175], v[196:199], 0
	v_mfma_f32_16x16x32_bf16 v[36:39], v[176:179], v[200:203], v[36:39]
	v_mfma_f32_16x16x32_bf16 v[20:23], v[172:175], v[204:207], 0
	v_mfma_f32_16x16x32_bf16 v[20:23], v[176:179], v[208:211], v[20:23]
	v_mfma_f32_16x16x32_bf16 v[16:19], v[180:183], v[204:207], 0
	v_mfma_f32_16x16x32_bf16 v[16:19], v[184:187], v[208:211], v[16:19]
	v_mfma_f32_16x16x32_bf16 v[0:3], v[180:183], v[216:219], 0
	v_mfma_f32_16x16x32_bf16 v[0:3], v[184:187], v[220:223], v[0:3]
	v_mfma_f32_16x16x32_bf16 v[4:7], v[172:175], v[216:219], 0
	v_mfma_f32_16x16x32_bf16 v[4:7], v[176:179], v[220:223], v[4:7]
	s_setprio 0
	s_barrier
	s_add_i32 s55, 0, 0x18000
	v_add_u32_e32 v155, s55, v148
	s_add_i32 s56, 0, 0x1c000
	ds_read_b128 v[156:159], v155
	ds_read_b128 v[160:163], v155 offset:1024
	ds_read_b128 v[164:167], v155 offset:2048
	ds_read_b128 v[168:171], v155 offset:3072
	v_add_u32_e32 v155, s56, v148
	ds_read_b128 v[172:175], v155
	ds_read_b128 v[176:179], v155 offset:1024
	ds_read_b128 v[180:183], v155 offset:2048
	ds_read_b128 v[184:187], v155 offset:3072
	s_add_u32 s40, s40, 0x40000
	s_addc_u32 s41, s41, 0
	s_mov_b32 m0, s35
	v_lshl_add_u64 v[228:229], s[40:41], 0, v[134:135]
	ds_read_b128 v[188:191], v154 offset:32768
	ds_read_b128 v[192:195], v154 offset:33792
	ds_read_b128 v[196:199], v154 offset:34816
	ds_read_b128 v[200:203], v154 offset:35840
	ds_read_b128 v[204:207], v154 offset:36864
	ds_read_b128 v[208:211], v154 offset:37888
	ds_read_b128 v[216:219], v154 offset:38912
	ds_read_b128 v[220:223], v154 offset:39936
	global_load_lds_dwordx4 v[228:229], off
	v_lshl_add_u64 v[228:229], s[40:41], 0, v[130:131]
	s_mov_b32 m0, s42
	s_nop 0
	global_load_lds_dwordx4 v[228:229], off
	s_waitcnt vmcnt(8)
	s_waitcnt lgkmcnt(0)
	s_barrier
	s_setprio 1
	s_waitcnt lgkmcnt(0)
	v_mfma_f32_16x16x32_bf16 v[124:127], v[156:159], v[188:191], v[124:127]
	v_mfma_f32_16x16x32_bf16 v[124:127], v[160:163], v[192:195], v[124:127]
	v_mfma_f32_16x16x32_bf16 v[120:123], v[164:167], v[188:191], v[120:123]
	v_mfma_f32_16x16x32_bf16 v[120:123], v[168:171], v[192:195], v[120:123]
	v_mfma_f32_16x16x32_bf16 v[104:107], v[164:167], v[196:199], v[104:107]
	v_mfma_f32_16x16x32_bf16 v[104:107], v[168:171], v[200:203], v[104:107]
	v_mfma_f32_16x16x32_bf16 v[108:111], v[156:159], v[196:199], v[108:111]
	v_mfma_f32_16x16x32_bf16 v[108:111], v[160:163], v[200:203], v[108:111]
	v_mfma_f32_16x16x32_bf16 v[92:95], v[156:159], v[204:207], v[92:95]
	v_mfma_f32_16x16x32_bf16 v[92:95], v[160:163], v[208:211], v[92:95]
	v_mfma_f32_16x16x32_bf16 v[88:91], v[164:167], v[204:207], v[88:91]
	v_mfma_f32_16x16x32_bf16 v[88:91], v[168:171], v[208:211], v[88:91]
	v_mfma_f32_16x16x32_bf16 v[72:75], v[164:167], v[216:219], v[72:75]
	v_mfma_f32_16x16x32_bf16 v[72:75], v[168:171], v[220:223], v[72:75]
	v_mfma_f32_16x16x32_bf16 v[76:79], v[156:159], v[216:219], v[76:79]
	v_mfma_f32_16x16x32_bf16 v[76:79], v[160:163], v[220:223], v[76:79]
	s_setprio 0
	s_setprio 1
	v_mfma_f32_16x16x32_bf16 v[116:119], v[172:175], v[188:191], v[116:119]
	v_mfma_f32_16x16x32_bf16 v[116:119], v[176:179], v[192:195], v[116:119]
	v_mfma_f32_16x16x32_bf16 v[112:115], v[180:183], v[188:191], v[112:115]
	v_mfma_f32_16x16x32_bf16 v[112:115], v[184:187], v[192:195], v[112:115]
	v_mfma_f32_16x16x32_bf16 v[96:99], v[180:183], v[196:199], v[96:99]
	v_mfma_f32_16x16x32_bf16 v[96:99], v[184:187], v[200:203], v[96:99]
	v_mfma_f32_16x16x32_bf16 v[100:103], v[172:175], v[196:199], v[100:103]
	v_mfma_f32_16x16x32_bf16 v[100:103], v[176:179], v[200:203], v[100:103]
	v_mfma_f32_16x16x32_bf16 v[84:87], v[172:175], v[204:207], v[84:87]
	v_mfma_f32_16x16x32_bf16 v[84:87], v[176:179], v[208:211], v[84:87]
	v_mfma_f32_16x16x32_bf16 v[80:83], v[180:183], v[204:207], v[80:83]
	v_mfma_f32_16x16x32_bf16 v[80:83], v[184:187], v[208:211], v[80:83]
	v_mfma_f32_16x16x32_bf16 v[64:67], v[180:183], v[216:219], v[64:67]
	v_mfma_f32_16x16x32_bf16 v[64:67], v[184:187], v[220:223], v[64:67]
	v_mfma_f32_16x16x32_bf16 v[68:71], v[172:175], v[216:219], v[68:71]
	v_mfma_f32_16x16x32_bf16 v[68:71], v[176:179], v[220:223], v[68:71]
	s_setprio 0
	s_barrier
	s_add_i32 s40, s55, s33
	v_lshl_add_u64 v[146:147], v[146:147], 0, s[18:19]
	s_mov_b32 m0, s40
	ds_read_b128 v[188:191], v154 offset:49152
	ds_read_b128 v[192:195], v154 offset:50176
	ds_read_b128 v[196:199], v154 offset:51200
	ds_read_b128 v[200:203], v154 offset:52224
	ds_read_b128 v[204:207], v154 offset:53248
	ds_read_b128 v[208:211], v154 offset:54272
	ds_read_b128 v[216:219], v154 offset:55296
	ds_read_b128 v[220:223], v154 offset:56320
	global_load_lds_dwordx4 v[146:147], off
	s_add_i32 m0, s40, 0x2000
	s_add_u32 s38, s38, 0x40080
	v_lshl_add_u64 v[146:147], v[212:213], 0, s[18:19]
	s_addc_u32 s39, s39, 0
	s_add_i32 s40, s56, s33
	global_load_lds_dwordx4 v[146:147], off
	v_lshl_add_u64 v[146:147], s[38:39], 0, v[132:133]
	s_mov_b32 m0, s40
	s_nop 0
	global_load_lds_dwordx4 v[146:147], off
	v_lshl_add_u64 v[146:147], s[38:39], 0, v[128:129]
	s_add_i32 m0, s40, 0x2000
	s_nop 0
	global_load_lds_dwordx4 v[146:147], off
	v_lshl_add_u64 v[146:147], v[224:225], 0, s[18:19]
	s_mov_b32 m0, s44
	s_nop 0
	global_load_lds_dwordx4 v[146:147], off
	v_lshl_add_u64 v[146:147], v[226:227], 0, s[18:19]
	s_mov_b32 m0, s45
	s_nop 0
	global_load_lds_dwordx4 v[146:147], off
	s_waitcnt vmcnt(8)
	s_waitcnt lgkmcnt(0)
	s_barrier
	s_setprio 1
	s_waitcnt lgkmcnt(0)
	v_mfma_f32_16x16x32_bf16 v[60:63], v[156:159], v[188:191], v[60:63]
	v_mfma_f32_16x16x32_bf16 v[60:63], v[160:163], v[192:195], v[60:63]
	v_mfma_f32_16x16x32_bf16 v[56:59], v[164:167], v[188:191], v[56:59]
	v_mfma_f32_16x16x32_bf16 v[56:59], v[168:171], v[192:195], v[56:59]
	v_mfma_f32_16x16x32_bf16 v[40:43], v[164:167], v[196:199], v[40:43]
	v_mfma_f32_16x16x32_bf16 v[40:43], v[168:171], v[200:203], v[40:43]
	v_mfma_f32_16x16x32_bf16 v[44:47], v[156:159], v[196:199], v[44:47]
	v_mfma_f32_16x16x32_bf16 v[44:47], v[160:163], v[200:203], v[44:47]
	v_mfma_f32_16x16x32_bf16 v[28:31], v[156:159], v[204:207], v[28:31]
	v_mfma_f32_16x16x32_bf16 v[28:31], v[160:163], v[208:211], v[28:31]
	v_mfma_f32_16x16x32_bf16 v[24:27], v[164:167], v[204:207], v[24:27]
	v_mfma_f32_16x16x32_bf16 v[24:27], v[168:171], v[208:211], v[24:27]
	v_mfma_f32_16x16x32_bf16 v[8:11], v[164:167], v[216:219], v[8:11]
	v_mfma_f32_16x16x32_bf16 v[8:11], v[168:171], v[220:223], v[8:11]
	v_mfma_f32_16x16x32_bf16 v[12:15], v[156:159], v[216:219], v[12:15]
	v_mfma_f32_16x16x32_bf16 v[12:15], v[160:163], v[220:223], v[12:15]
	s_setprio 0
	s_setprio 1
	v_mfma_f32_16x16x32_bf16 v[52:55], v[172:175], v[188:191], v[52:55]
	v_mfma_f32_16x16x32_bf16 v[52:55], v[176:179], v[192:195], v[52:55]
	v_mfma_f32_16x16x32_bf16 v[48:51], v[180:183], v[188:191], v[48:51]
	v_mfma_f32_16x16x32_bf16 v[48:51], v[184:187], v[192:195], v[48:51]
	v_mfma_f32_16x16x32_bf16 v[32:35], v[180:183], v[196:199], v[32:35]
	v_mfma_f32_16x16x32_bf16 v[32:35], v[184:187], v[200:203], v[32:35]
	v_mfma_f32_16x16x32_bf16 v[36:39], v[172:175], v[196:199], v[36:39]
	v_mfma_f32_16x16x32_bf16 v[36:39], v[176:179], v[200:203], v[36:39]
	v_mfma_f32_16x16x32_bf16 v[20:23], v[172:175], v[204:207], v[20:23]
	v_mfma_f32_16x16x32_bf16 v[20:23], v[176:179], v[208:211], v[20:23]
	v_mfma_f32_16x16x32_bf16 v[16:19], v[180:183], v[204:207], v[16:19]
	v_mfma_f32_16x16x32_bf16 v[16:19], v[184:187], v[208:211], v[16:19]
	v_mfma_f32_16x16x32_bf16 v[0:3], v[180:183], v[216:219], v[0:3]
	v_mfma_f32_16x16x32_bf16 v[0:3], v[184:187], v[220:223], v[0:3]
	v_mfma_f32_16x16x32_bf16 v[4:7], v[172:175], v[216:219], v[4:7]
	v_mfma_f32_16x16x32_bf16 v[4:7], v[176:179], v[220:223], v[4:7]
	s_setprio 0
	s_barrier
	s_add_i32 s54, s54, 2
	s_add_u32 s36, s36, 0x100
	s_addc_u32 s37, s37, 0
	s_add_u32 s52, s52, 0x100
	s_addc_u32 s53, s53, 0

.LBB0_827:
	s_ashr_i32 s27, s26, 31
	s_lshl_b64 s[28:29], s[26:27], 21
	s_add_u32 s28, s60, s28
	s_addc_u32 s29, s61, s29
	s_and_b64 s[30:31], s[4:5], exec
	s_cselect_b32 s27, s29, s39
	s_cselect_b32 s54, s28, s38
	s_ashr_i32 s25, s24, 31
	s_lshl_b64 s[30:31], s[24:25], 21
	s_add_u32 s30, s12, s30
	s_addc_u32 s31, s13, s31
	s_and_b64 s[42:43], s[4:5], exec
	s_cselect_b32 s25, s31, s41
	s_cselect_b32 s55, s30, s40
	s_add_u32 s38, s38, 0x100080
	s_addc_u32 s39, s39, 0
	s_add_u32 s56, s40, 0x100
	s_addc_u32 s57, s41, 0
	s_mov_b32 s58, -2
	ds_read_b128 v[142:145], v195
	ds_read_b128 v[146:149], v195 offset:1024
	ds_read_b128 v[150:153], v195 offset:2048
	ds_read_b128 v[154:157], v195 offset:3072
	ds_read_b128 v[158:161], v196
	ds_read_b128 v[162:165], v196 offset:1024
	ds_read_b128 v[166:169], v196 offset:2048
	ds_read_b128 v[170:173], v196 offset:3072
	s_add_u32 s40, s38, 0xfff00080
	s_addc_u32 s41, s39, -1
	s_cmp_eq_u32 s58, 60
	s_cselect_b32 s43, s27, s41
	s_cselect_b32 s42, s54, s40
	s_cselect_b32 s41, s25, s57
	s_cselect_b32 s40, s55, s56
	v_lshl_add_u64 v[190:191], s[38:39], 0, v[134:135]
	s_add_i32 m0, s2, 0xc000
	ds_read_b128 v[174:177], v197
	ds_read_b128 v[178:181], v197 offset:1024
	ds_read_b128 v[182:185], v197 offset:2048
	ds_read_b128 v[186:189], v197 offset:3072
	ds_read_b128 v[198:201], v197 offset:4096
	ds_read_b128 v[202:205], v197 offset:5120
	ds_read_b128 v[206:209], v197 offset:6144
	ds_read_b128 v[210:213], v197 offset:7168
	global_load_lds_dwordx4 v[190:191], off
	v_lshl_add_u64 v[190:191], s[38:39], 0, v[136:137]
	s_add_i32 m0, s2, 0xe000
	s_nop 0
	global_load_lds_dwordx4 v[190:191], off
	s_waitcnt vmcnt(8)
	s_waitcnt lgkmcnt(0)
	s_barrier
	s_setprio 1
	s_waitcnt lgkmcnt(0)
	v_mfma_f32_16x16x32_bf16 v[124:127], v[142:145], v[174:177], 0
	v_mfma_f32_16x16x32_bf16 v[124:127], v[146:149], v[178:181], v[124:127]
	v_mfma_f32_16x16x32_bf16 v[120:123], v[150:153], v[174:177], 0
	v_mfma_f32_16x16x32_bf16 v[120:123], v[154:157], v[178:181], v[120:123]
	v_mfma_f32_16x16x32_bf16 v[104:107], v[150:153], v[182:185], 0
	v_mfma_f32_16x16x32_bf16 v[104:107], v[154:157], v[186:189], v[104:107]
	v_mfma_f32_16x16x32_bf16 v[108:111], v[142:145], v[182:185], 0
	v_mfma_f32_16x16x32_bf16 v[108:111], v[146:149], v[186:189], v[108:111]
	v_mfma_f32_16x16x32_bf16 v[92:95], v[142:145], v[198:201], 0
	v_mfma_f32_16x16x32_bf16 v[92:95], v[146:149], v[202:205], v[92:95]
	v_mfma_f32_16x16x32_bf16 v[88:91], v[150:153], v[198:201], 0
	v_mfma_f32_16x16x32_bf16 v[88:91], v[154:157], v[202:205], v[88:91]
	v_mfma_f32_16x16x32_bf16 v[72:75], v[150:153], v[206:209], 0
	v_mfma_f32_16x16x32_bf16 v[72:75], v[154:157], v[210:213], v[72:75]
	v_mfma_f32_16x16x32_bf16 v[76:79], v[142:145], v[206:209], 0
	v_mfma_f32_16x16x32_bf16 v[76:79], v[146:149], v[210:213], v[76:79]
	s_setprio 0
	s_setprio 1
	v_mfma_f32_16x16x32_bf16 v[116:119], v[158:161], v[174:177], 0
	v_mfma_f32_16x16x32_bf16 v[116:119], v[162:165], v[178:181], v[116:119]
	v_mfma_f32_16x16x32_bf16 v[112:115], v[166:169], v[174:177], 0
	v_mfma_f32_16x16x32_bf16 v[112:115], v[170:173], v[178:181], v[112:115]
	v_mfma_f32_16x16x32_bf16 v[96:99], v[166:169], v[182:185], 0
	v_mfma_f32_16x16x32_bf16 v[96:99], v[170:173], v[186:189], v[96:99]
	v_mfma_f32_16x16x32_bf16 v[100:103], v[158:161], v[182:185], 0
	v_mfma_f32_16x16x32_bf16 v[100:103], v[162:165], v[186:189], v[100:103]
	v_mfma_f32_16x16x32_bf16 v[84:87], v[158:161], v[198:201], 0
	v_mfma_f32_16x16x32_bf16 v[84:87], v[162:165], v[202:205], v[84:87]
	v_mfma_f32_16x16x32_bf16 v[80:83], v[166:169], v[198:201], 0
	v_mfma_f32_16x16x32_bf16 v[80:83], v[170:173], v[202:205], v[80:83]
	v_mfma_f32_16x16x32_bf16 v[64:67], v[166:169], v[206:209], 0
	v_mfma_f32_16x16x32_bf16 v[64:67], v[170:173], v[210:213], v[64:67]
	v_mfma_f32_16x16x32_bf16 v[68:71], v[158:161], v[206:209], 0
	v_mfma_f32_16x16x32_bf16 v[68:71], v[162:165], v[210:213], v[68:71]
	s_setprio 0
	s_barrier
	s_add_i32 s59, s46, s3
	v_lshl_add_u64 v[190:191], s[40:41], 0, v[128:129]
	s_mov_b32 m0, s59
	ds_read_b128 v[174:177], v197 offset:16384
	ds_read_b128 v[178:181], v197 offset:17408
	ds_read_b128 v[182:185], v197 offset:18432
	ds_read_b128 v[186:189], v197 offset:19456
	ds_read_b128 v[198:201], v197 offset:20480
	ds_read_b128 v[202:205], v197 offset:21504
	ds_read_b128 v[206:209], v197 offset:22528
	ds_read_b128 v[210:213], v197 offset:23552
	global_load_lds_dwordx4 v[190:191], off
	s_add_i32 m0, s59, 0x2000
	s_add_u32 s62, s40, 0x100000
	v_lshl_add_u64 v[214:215], s[40:41], 0, v[130:131]
	s_addc_u32 s63, s41, 0
	s_add_i32 s59, s47, s3
	global_load_lds_dwordx4 v[214:215], off
	v_lshl_add_u64 v[216:217], s[62:63], 0, v[128:129]
	s_mov_b32 m0, s59
	v_lshl_add_u64 v[218:219], s[42:43], 0, v[130:131]
	global_load_lds_dwordx4 v[216:217], off
	v_lshl_add_u64 v[216:217], s[62:63], 0, v[130:131]
	s_add_i32 m0, s59, 0x2000
	s_nop 0
	global_load_lds_dwordx4 v[216:217], off
	v_lshl_add_u64 v[216:217], s[42:43], 0, v[128:129]
	s_mov_b32 m0, s2
	s_nop 0
	global_load_lds_dwordx4 v[216:217], off
	s_mov_b32 m0, s33
	s_nop 0
	global_load_lds_dwordx4 v[218:219], off
	s_waitcnt vmcnt(8)
	s_waitcnt lgkmcnt(0)
	s_barrier
	s_setprio 1
	s_waitcnt lgkmcnt(0)
	v_mfma_f32_16x16x32_bf16 v[60:63], v[142:145], v[174:177], 0
	v_mfma_f32_16x16x32_bf16 v[60:63], v[146:149], v[178:181], v[60:63]
	v_mfma_f32_16x16x32_bf16 v[56:59], v[150:153], v[174:177], 0
	v_mfma_f32_16x16x32_bf16 v[56:59], v[154:157], v[178:181], v[56:59]
	v_mfma_f32_16x16x32_bf16 v[40:43], v[150:153], v[182:185], 0
	v_mfma_f32_16x16x32_bf16 v[40:43], v[154:157], v[186:189], v[40:43]
	v_mfma_f32_16x16x32_bf16 v[44:47], v[142:145], v[182:185], 0
	v_mfma_f32_16x16x32_bf16 v[44:47], v[146:149], v[186:189], v[44:47]
	v_mfma_f32_16x16x32_bf16 v[28:31], v[142:145], v[198:201], 0
	v_mfma_f32_16x16x32_bf16 v[28:31], v[146:149], v[202:205], v[28:31]
	v_mfma_f32_16x16x32_bf16 v[24:27], v[150:153], v[198:201], 0
	v_mfma_f32_16x16x32_bf16 v[24:27], v[154:157], v[202:205], v[24:27]
	v_mfma_f32_16x16x32_bf16 v[8:11], v[150:153], v[206:209], 0
	v_mfma_f32_16x16x32_bf16 v[8:11], v[154:157], v[210:213], v[8:11]
	v_mfma_f32_16x16x32_bf16 v[12:15], v[142:145], v[206:209], 0
	v_mfma_f32_16x16x32_bf16 v[12:15], v[146:149], v[210:213], v[12:15]
	s_setprio 0
	s_setprio 1
	v_mfma_f32_16x16x32_bf16 v[52:55], v[158:161], v[174:177], 0
	v_mfma_f32_16x16x32_bf16 v[52:55], v[162:165], v[178:181], v[52:55]
	v_mfma_f32_16x16x32_bf16 v[48:51], v[166:169], v[174:177], 0
	v_mfma_f32_16x16x32_bf16 v[48:51], v[170:173], v[178:181], v[48:51]
	v_mfma_f32_16x16x32_bf16 v[32:35], v[166:169], v[182:185], 0
	v_mfma_f32_16x16x32_bf16 v[32:35], v[170:173], v[186:189], v[32:35]
	v_mfma_f32_16x16x32_bf16 v[36:39], v[158:161], v[182:185], 0
	v_mfma_f32_16x16x32_bf16 v[36:39], v[162:165], v[186:189], v[36:39]
	v_mfma_f32_16x16x32_bf16 v[20:23], v[158:161], v[198:201], 0
	v_mfma_f32_16x16x32_bf16 v[20:23], v[162:165], v[202:205], v[20:23]
	v_mfma_f32_16x16x32_bf16 v[16:19], v[166:169], v[198:201], 0
	v_mfma_f32_16x16x32_bf16 v[16:19], v[170:173], v[202:205], v[16:19]
	v_mfma_f32_16x16x32_bf16 v[0:3], v[166:169], v[206:209], 0
	v_mfma_f32_16x16x32_bf16 v[0:3], v[170:173], v[210:213], v[0:3]
	v_mfma_f32_16x16x32_bf16 v[4:7], v[158:161], v[206:209], 0
	v_mfma_f32_16x16x32_bf16 v[4:7], v[162:165], v[210:213], v[4:7]
	s_setprio 0
	s_barrier
	s_add_i32 s59, 0, 0x18000
	s_add_i32 s62, 0, 0x1c000
	v_add_u32_e32 v154, s59, v192
	v_add_u32_e32 v170, s62, v192
	ds_read_b128 v[142:145], v154
	ds_read_b128 v[146:149], v154 offset:1024
	ds_read_b128 v[150:153], v154 offset:2048
	ds_read_b128 v[154:157], v154 offset:3072
	ds_read_b128 v[158:161], v170
	ds_read_b128 v[162:165], v170 offset:1024
	ds_read_b128 v[166:169], v170 offset:2048
	ds_read_b128 v[170:173], v170 offset:3072
	s_add_u32 s42, s42, 0x100000
	s_addc_u32 s43, s43, 0
	s_mov_b32 m0, s34
	v_lshl_add_u64 v[220:221], s[42:43], 0, v[128:129]
	ds_read_b128 v[174:177], v197 offset:32768
	ds_read_b128 v[178:181], v197 offset:33792
	ds_read_b128 v[182:185], v197 offset:34816
	ds_read_b128 v[186:189], v197 offset:35840
	ds_read_b128 v[198:201], v197 offset:36864
	ds_read_b128 v[202:205], v197 offset:37888
	ds_read_b128 v[206:209], v197 offset:38912
	ds_read_b128 v[210:213], v197 offset:39936
	global_load_lds_dwordx4 v[220:221], off
	v_lshl_add_u64 v[220:221], s[42:43], 0, v[130:131]
	s_mov_b32 m0, s35
	s_nop 0
	global_load_lds_dwordx4 v[220:221], off
	s_waitcnt vmcnt(8)
	s_waitcnt lgkmcnt(0)
	s_barrier
	s_setprio 1
	s_waitcnt lgkmcnt(0)
	v_mfma_f32_16x16x32_bf16 v[124:127], v[142:145], v[174:177], v[124:127]
	v_mfma_f32_16x16x32_bf16 v[124:127], v[146:149], v[178:181], v[124:127]
	v_mfma_f32_16x16x32_bf16 v[120:123], v[150:153], v[174:177], v[120:123]
	v_mfma_f32_16x16x32_bf16 v[120:123], v[154:157], v[178:181], v[120:123]
	v_mfma_f32_16x16x32_bf16 v[104:107], v[150:153], v[182:185], v[104:107]
	v_mfma_f32_16x16x32_bf16 v[104:107], v[154:157], v[186:189], v[104:107]
	v_mfma_f32_16x16x32_bf16 v[108:111], v[142:145], v[182:185], v[108:111]
	v_mfma_f32_16x16x32_bf16 v[108:111], v[146:149], v[186:189], v[108:111]
	v_mfma_f32_16x16x32_bf16 v[92:95], v[142:145], v[198:201], v[92:95]
	v_mfma_f32_16x16x32_bf16 v[92:95], v[146:149], v[202:205], v[92:95]
	v_mfma_f32_16x16x32_bf16 v[88:91], v[150:153], v[198:201], v[88:91]
	v_mfma_f32_16x16x32_bf16 v[88:91], v[154:157], v[202:205], v[88:91]
	v_mfma_f32_16x16x32_bf16 v[72:75], v[150:153], v[206:209], v[72:75]
	v_mfma_f32_16x16x32_bf16 v[72:75], v[154:157], v[210:213], v[72:75]
	v_mfma_f32_16x16x32_bf16 v[76:79], v[142:145], v[206:209], v[76:79]
	v_mfma_f32_16x16x32_bf16 v[76:79], v[146:149], v[210:213], v[76:79]
	s_setprio 0
	s_setprio 1
	v_mfma_f32_16x16x32_bf16 v[116:119], v[158:161], v[174:177], v[116:119]
	v_mfma_f32_16x16x32_bf16 v[116:119], v[162:165], v[178:181], v[116:119]
	v_mfma_f32_16x16x32_bf16 v[112:115], v[166:169], v[174:177], v[112:115]
	v_mfma_f32_16x16x32_bf16 v[112:115], v[170:173], v[178:181], v[112:115]
	v_mfma_f32_16x16x32_bf16 v[96:99], v[166:169], v[182:185], v[96:99]
	v_mfma_f32_16x16x32_bf16 v[96:99], v[170:173], v[186:189], v[96:99]
	v_mfma_f32_16x16x32_bf16 v[100:103], v[158:161], v[182:185], v[100:103]
	v_mfma_f32_16x16x32_bf16 v[100:103], v[162:165], v[186:189], v[100:103]
	v_mfma_f32_16x16x32_bf16 v[84:87], v[158:161], v[198:201], v[84:87]
	v_mfma_f32_16x16x32_bf16 v[84:87], v[162:165], v[202:205], v[84:87]
	v_mfma_f32_16x16x32_bf16 v[80:83], v[166:169], v[198:201], v[80:83]
	v_mfma_f32_16x16x32_bf16 v[80:83], v[170:173], v[202:205], v[80:83]
	v_mfma_f32_16x16x32_bf16 v[64:67], v[166:169], v[206:209], v[64:67]
	v_mfma_f32_16x16x32_bf16 v[64:67], v[170:173], v[210:213], v[64:67]
	v_mfma_f32_16x16x32_bf16 v[68:71], v[158:161], v[206:209], v[68:71]
	v_mfma_f32_16x16x32_bf16 v[68:71], v[162:165], v[210:213], v[68:71]
	s_setprio 0
	s_barrier
	s_add_i32 s42, s59, s3
	v_lshl_add_u64 v[190:191], v[190:191], 0, s[8:9]
	s_mov_b32 m0, s42
	ds_read_b128 v[174:177], v197 offset:49152
	ds_read_b128 v[178:181], v197 offset:50176
	ds_read_b128 v[182:185], v197 offset:51200
	ds_read_b128 v[186:189], v197 offset:52224
	ds_read_b128 v[198:201], v197 offset:53248
	ds_read_b128 v[202:205], v197 offset:54272
	ds_read_b128 v[206:209], v197 offset:55296
	ds_read_b128 v[210:213], v197 offset:56320
	global_load_lds_dwordx4 v[190:191], off
	s_add_i32 m0, s42, 0x2000
	s_add_u32 s40, s40, 0x100080
	v_lshl_add_u64 v[190:191], v[214:215], 0, s[8:9]
	s_addc_u32 s41, s41, 0
	s_add_i32 s42, s62, s3
	global_load_lds_dwordx4 v[190:191], off
	v_lshl_add_u64 v[190:191], s[40:41], 0, v[128:129]
	s_mov_b32 m0, s42
	s_nop 0
	global_load_lds_dwordx4 v[190:191], off
	v_lshl_add_u64 v[190:191], s[40:41], 0, v[130:131]
	s_add_i32 m0, s42, 0x2000
	s_nop 0
	global_load_lds_dwordx4 v[190:191], off
	v_lshl_add_u64 v[190:191], v[216:217], 0, s[8:9]
	s_mov_b32 m0, s44
	s_nop 0
	global_load_lds_dwordx4 v[190:191], off
	v_lshl_add_u64 v[190:191], v[218:219], 0, s[8:9]
	s_mov_b32 m0, s45
	s_nop 0
	global_load_lds_dwordx4 v[190:191], off
	s_waitcnt vmcnt(8)
	s_waitcnt lgkmcnt(0)
	s_barrier
	s_setprio 1
	s_waitcnt lgkmcnt(0)
	v_mfma_f32_16x16x32_bf16 v[60:63], v[142:145], v[174:177], v[60:63]
	v_mfma_f32_16x16x32_bf16 v[60:63], v[146:149], v[178:181], v[60:63]
	v_mfma_f32_16x16x32_bf16 v[56:59], v[150:153], v[174:177], v[56:59]
	v_mfma_f32_16x16x32_bf16 v[56:59], v[154:157], v[178:181], v[56:59]
	v_mfma_f32_16x16x32_bf16 v[40:43], v[150:153], v[182:185], v[40:43]
	v_mfma_f32_16x16x32_bf16 v[40:43], v[154:157], v[186:189], v[40:43]
	v_mfma_f32_16x16x32_bf16 v[44:47], v[142:145], v[182:185], v[44:47]
	v_mfma_f32_16x16x32_bf16 v[44:47], v[146:149], v[186:189], v[44:47]
	v_mfma_f32_16x16x32_bf16 v[28:31], v[142:145], v[198:201], v[28:31]
	v_mfma_f32_16x16x32_bf16 v[28:31], v[146:149], v[202:205], v[28:31]
	v_mfma_f32_16x16x32_bf16 v[24:27], v[150:153], v[198:201], v[24:27]
	v_mfma_f32_16x16x32_bf16 v[24:27], v[154:157], v[202:205], v[24:27]
	v_mfma_f32_16x16x32_bf16 v[8:11], v[150:153], v[206:209], v[8:11]
	v_mfma_f32_16x16x32_bf16 v[8:11], v[154:157], v[210:213], v[8:11]
	v_mfma_f32_16x16x32_bf16 v[12:15], v[142:145], v[206:209], v[12:15]
	v_mfma_f32_16x16x32_bf16 v[12:15], v[146:149], v[210:213], v[12:15]
	s_setprio 0
	s_setprio 1
	v_mfma_f32_16x16x32_bf16 v[52:55], v[158:161], v[174:177], v[52:55]
	v_mfma_f32_16x16x32_bf16 v[52:55], v[162:165], v[178:181], v[52:55]
	v_mfma_f32_16x16x32_bf16 v[48:51], v[166:169], v[174:177], v[48:51]
	v_mfma_f32_16x16x32_bf16 v[48:51], v[170:173], v[178:181], v[48:51]
	v_mfma_f32_16x16x32_bf16 v[32:35], v[166:169], v[182:185], v[32:35]
	v_mfma_f32_16x16x32_bf16 v[32:35], v[170:173], v[186:189], v[32:35]
	v_mfma_f32_16x16x32_bf16 v[36:39], v[158:161], v[182:185], v[36:39]
	v_mfma_f32_16x16x32_bf16 v[36:39], v[162:165], v[186:189], v[36:39]
	v_mfma_f32_16x16x32_bf16 v[20:23], v[158:161], v[198:201], v[20:23]
	v_mfma_f32_16x16x32_bf16 v[20:23], v[162:165], v[202:205], v[20:23]
	v_mfma_f32_16x16x32_bf16 v[16:19], v[166:169], v[198:201], v[16:19]
	v_mfma_f32_16x16x32_bf16 v[16:19], v[170:173], v[202:205], v[16:19]
	v_mfma_f32_16x16x32_bf16 v[0:3], v[166:169], v[206:209], v[0:3]
	v_mfma_f32_16x16x32_bf16 v[0:3], v[170:173], v[210:213], v[0:3]
	v_mfma_f32_16x16x32_bf16 v[4:7], v[158:161], v[206:209], v[4:7]
	v_mfma_f32_16x16x32_bf16 v[4:7], v[162:165], v[210:213], v[4:7]
	s_setprio 0
	s_barrier
	s_add_i32 s58, s58, 2
	s_add_u32 s38, s38, 0x100
	s_addc_u32 s39, s39, 0
	s_add_u32 s56, s56, 0x100
	s_addc_u32 s57, s57, 0
